# k20 plus K-loop back-edge rotation and hoisted B read bases in the proj and gate-up loops
# speedup vs baseline: 1.0027x; 1.0027x over previous
.Lpj_skip2_p:
	s_mov_b32 s32, 0
	s_waitcnt lgkmcnt(0)
	s_barrier
	s_setprio 1
	v_mfma_f32_16x16x32_bf16 v[64:67], v[154:157], v[196:199], 0
	v_mfma_f32_16x16x32_bf16 v[60:63], v[172:175], v[196:199], 0
	v_mfma_f32_16x16x32_bf16 v[52:55], v[154:157], v[204:207], 0
	v_mfma_f32_16x16x32_bf16 v[44:47], v[172:175], v[204:207], 0
	v_mfma_f32_16x16x32_bf16 v[36:39], v[154:157], v[212:215], 0
	v_mfma_f32_16x16x32_bf16 v[28:31], v[172:175], v[212:215], 0
	v_mfma_f32_16x16x32_bf16 v[20:23], v[154:157], v[220:223], 0
	v_mfma_f32_16x16x32_bf16 v[12:15], v[172:175], v[220:223], 0
	v_mfma_f32_16x16x32_bf16 v[64:67], v[168:171], v[200:203], v[64:67]
	v_mfma_f32_16x16x32_bf16 v[60:63], v[176:179], v[200:203], v[60:63]
	v_mfma_f32_16x16x32_bf16 v[52:55], v[168:171], v[208:211], v[52:55]
	v_mfma_f32_16x16x32_bf16 v[44:47], v[176:179], v[208:211], v[44:47]
	v_mfma_f32_16x16x32_bf16 v[36:39], v[168:171], v[216:219], v[36:39]
	v_mfma_f32_16x16x32_bf16 v[28:31], v[176:179], v[216:219], v[28:31]
	v_mfma_f32_16x16x32_bf16 v[20:23], v[168:171], v[224:227], v[20:23]
	v_mfma_f32_16x16x32_bf16 v[12:15], v[176:179], v[224:227], v[12:15]
	v_mfma_f32_16x16x32_bf16 v[56:59], v[180:183], v[196:199], 0
	v_mfma_f32_16x16x32_bf16 v[48:51], v[188:191], v[196:199], 0
	v_mfma_f32_16x16x32_bf16 v[40:43], v[180:183], v[204:207], 0
	v_mfma_f32_16x16x32_bf16 v[32:35], v[188:191], v[204:207], 0
	v_mfma_f32_16x16x32_bf16 v[24:27], v[180:183], v[212:215], 0
	v_mfma_f32_16x16x32_bf16 v[16:19], v[188:191], v[212:215], 0
	v_mfma_f32_16x16x32_bf16 v[8:11], v[180:183], v[220:223], 0
	v_mfma_f32_16x16x32_bf16 v[4:7], v[188:191], v[220:223], 0
	v_mfma_f32_16x16x32_bf16 v[56:59], v[184:187], v[200:203], v[56:59]
	v_mfma_f32_16x16x32_bf16 v[48:51], v[192:195], v[200:203], v[48:51]
	v_mfma_f32_16x16x32_bf16 v[40:43], v[184:187], v[208:211], v[40:43]
	v_mfma_f32_16x16x32_bf16 v[32:35], v[192:195], v[208:211], v[32:35]
	v_mfma_f32_16x16x32_bf16 v[24:27], v[184:187], v[216:219], v[24:27]
	v_mfma_f32_16x16x32_bf16 v[16:19], v[192:195], v[216:219], v[16:19]
	v_mfma_f32_16x16x32_bf16 v[8:11], v[184:187], v[224:227], v[8:11]
	v_mfma_f32_16x16x32_bf16 v[4:7], v[192:195], v[224:227], v[4:7]
	s_barrier
	s_setprio 0
	s_add_i32 s33, 0, 0x18000
	s_add_i32 s43, 0, 0x1c000
	ds_read_b128 v[154:157], v229 offset:32768
	ds_read_b128 v[168:171], v229 offset:33792
	ds_read_b128 v[172:175], v229 offset:34816
	ds_read_b128 v[176:179], v229 offset:35840
	ds_read_b128 v[180:183], v229 offset:49152
	ds_read_b128 v[184:187], v229 offset:50176
	ds_read_b128 v[188:191], v229 offset:51200
	ds_read_b128 v[192:195], v229 offset:52224
	s_add_u32 s48, s48, 0x80000
	s_addc_u32 s49, s49, 0
	s_mov_b32 m0, s14
	ds_read_b128 v[196:199], v167 offset:32768
	ds_read_b128 v[200:203], v167 offset:33792
	ds_read_b128 v[204:207], v167 offset:34816
	ds_read_b128 v[208:211], v167 offset:35840
	ds_read_b128 v[212:215], v167 offset:36864
	ds_read_b128 v[216:219], v167 offset:37888
	ds_read_b128 v[220:223], v167 offset:38912
	ds_read_b128 v[224:227], v167 offset:39936
	global_load_lds_dwordx4 v134, s[48:49]
	s_mov_b32 m0, s15
	s_nop 0
	global_load_lds_dwordx4 v132, s[48:49]
	s_waitcnt vmcnt(8)
	s_waitcnt lgkmcnt(0)
	s_barrier
	s_setprio 1
	v_mfma_f32_16x16x32_bf16 v[128:131], v[154:157], v[196:199], v[128:131]
	v_mfma_f32_16x16x32_bf16 v[124:127], v[172:175], v[196:199], v[124:127]
	v_mfma_f32_16x16x32_bf16 v[116:119], v[154:157], v[204:207], v[116:119]
	v_mfma_f32_16x16x32_bf16 v[108:111], v[172:175], v[204:207], v[108:111]
	v_mfma_f32_16x16x32_bf16 v[100:103], v[154:157], v[212:215], v[100:103]
	v_mfma_f32_16x16x32_bf16 v[92:95], v[172:175], v[212:215], v[92:95]
	v_mfma_f32_16x16x32_bf16 v[84:87], v[154:157], v[220:223], v[84:87]
	v_mfma_f32_16x16x32_bf16 v[76:79], v[172:175], v[220:223], v[76:79]
	v_mfma_f32_16x16x32_bf16 v[128:131], v[168:171], v[200:203], v[128:131]
	v_mfma_f32_16x16x32_bf16 v[124:127], v[176:179], v[200:203], v[124:127]
	v_mfma_f32_16x16x32_bf16 v[116:119], v[168:171], v[208:211], v[116:119]
	v_mfma_f32_16x16x32_bf16 v[108:111], v[176:179], v[208:211], v[108:111]
	v_mfma_f32_16x16x32_bf16 v[100:103], v[168:171], v[216:219], v[100:103]
	v_mfma_f32_16x16x32_bf16 v[92:95], v[176:179], v[216:219], v[92:95]
	v_mfma_f32_16x16x32_bf16 v[84:87], v[168:171], v[224:227], v[84:87]
	v_mfma_f32_16x16x32_bf16 v[76:79], v[176:179], v[224:227], v[76:79]
	v_mfma_f32_16x16x32_bf16 v[120:123], v[180:183], v[196:199], v[120:123]
	v_mfma_f32_16x16x32_bf16 v[112:115], v[188:191], v[196:199], v[112:115]
	v_mfma_f32_16x16x32_bf16 v[104:107], v[180:183], v[204:207], v[104:107]
	v_mfma_f32_16x16x32_bf16 v[96:99], v[188:191], v[204:207], v[96:99]
	v_mfma_f32_16x16x32_bf16 v[88:91], v[180:183], v[212:215], v[88:91]
	v_mfma_f32_16x16x32_bf16 v[80:83], v[188:191], v[212:215], v[80:83]
	v_mfma_f32_16x16x32_bf16 v[72:75], v[180:183], v[220:223], v[72:75]
	v_mfma_f32_16x16x32_bf16 v[68:71], v[188:191], v[220:223], v[68:71]
	v_mfma_f32_16x16x32_bf16 v[120:123], v[184:187], v[200:203], v[120:123]
	v_mfma_f32_16x16x32_bf16 v[112:115], v[192:195], v[200:203], v[112:115]
	v_mfma_f32_16x16x32_bf16 v[104:107], v[184:187], v[208:211], v[104:107]
	v_mfma_f32_16x16x32_bf16 v[96:99], v[192:195], v[208:211], v[96:99]
	v_mfma_f32_16x16x32_bf16 v[88:91], v[184:187], v[216:219], v[88:91]
	v_mfma_f32_16x16x32_bf16 v[80:83], v[192:195], v[216:219], v[80:83]
	v_mfma_f32_16x16x32_bf16 v[72:75], v[184:187], v[224:227], v[72:75]
	v_mfma_f32_16x16x32_bf16 v[68:71], v[192:195], v[224:227], v[68:71]
	s_barrier
	s_setprio 0
	s_add_i32 s33, s33, s10
	s_mov_b32 m0, s33
	ds_read_b128 v[196:199], v167 offset:49152
	ds_read_b128 v[200:203], v167 offset:50176
	ds_read_b128 v[204:207], v167 offset:51200
	ds_read_b128 v[208:211], v167 offset:52224
	ds_read_b128 v[212:215], v167 offset:53248
	ds_read_b128 v[216:219], v167 offset:54272
	ds_read_b128 v[220:223], v167 offset:55296
	ds_read_b128 v[224:227], v167 offset:56320
	s_add_u32 s100, s46, 0x80
	s_addc_u32 s101, s47, 0
	global_load_lds_dwordx4 v2, s[100:101]
	s_add_i32 m0, s33, 0x2000
	s_add_u32 s46, s46, 0x80080
	s_addc_u32 s47, s47, 0
	s_add_i32 s33, s43, s10
	s_add_u32 s100, s46, 0xfff80000
	s_addc_u32 s101, s47, -1
	global_load_lds_dwordx4 v0, s[100:101]
	s_mov_b32 m0, s33
	s_nop 0
	global_load_lds_dwordx4 v2, s[46:47]
	s_add_i32 m0, s33, 0x2000
	s_nop 0
	global_load_lds_dwordx4 v0, s[46:47]
	s_mov_b32 m0, s16
	s_nop 0
	s_add_u32 s100, s48, 0xfff80080
	s_addc_u32 s101, s49, -1
	global_load_lds_dwordx4 v134, s[100:101]
	s_mov_b32 m0, s17
	s_nop 0
	s_add_u32 s100, s48, 0xfff80080
	s_addc_u32 s101, s49, -1
	global_load_lds_dwordx4 v132, s[100:101]
	s_add_i32 s35, s35, 2
	s_add_u32 s31, s31, 0x100
	s_addc_u32 s34, s34, 0
	s_add_u32 s44, s44, 0x100
	s_addc_u32 s45, s45, 0
	s_add_u32 s33, s44, 0xfff80080
	s_addc_u32 s43, s45, -1
	s_cmp_eq_u32 s35, 28
	s_cselect_b32 s49, s27, s43
	s_cselect_b32 s48, s28, s33
	s_cselect_b32 s47, s25, s34
	s_cselect_b32 s46, s29, s31
	s_waitcnt vmcnt(8)
	s_waitcnt lgkmcnt(0)
	s_barrier
	s_setprio 1
	v_mfma_f32_16x16x32_bf16 v[64:67], v[154:157], v[196:199], v[64:67]
	v_mfma_f32_16x16x32_bf16 v[60:63], v[172:175], v[196:199], v[60:63]
	v_mfma_f32_16x16x32_bf16 v[52:55], v[154:157], v[204:207], v[52:55]
	v_mfma_f32_16x16x32_bf16 v[44:47], v[172:175], v[204:207], v[44:47]
	v_mfma_f32_16x16x32_bf16 v[36:39], v[154:157], v[212:215], v[36:39]
	v_mfma_f32_16x16x32_bf16 v[28:31], v[172:175], v[212:215], v[28:31]
	v_mfma_f32_16x16x32_bf16 v[20:23], v[154:157], v[220:223], v[20:23]
	v_mfma_f32_16x16x32_bf16 v[12:15], v[172:175], v[220:223], v[12:15]
	v_mfma_f32_16x16x32_bf16 v[64:67], v[168:171], v[200:203], v[64:67]
	v_mfma_f32_16x16x32_bf16 v[60:63], v[176:179], v[200:203], v[60:63]
	v_mfma_f32_16x16x32_bf16 v[52:55], v[168:171], v[208:211], v[52:55]
	v_mfma_f32_16x16x32_bf16 v[44:47], v[176:179], v[208:211], v[44:47]
	v_mfma_f32_16x16x32_bf16 v[36:39], v[168:171], v[216:219], v[36:39]
	v_mfma_f32_16x16x32_bf16 v[28:31], v[176:179], v[216:219], v[28:31]
	v_mfma_f32_16x16x32_bf16 v[20:23], v[168:171], v[224:227], v[20:23]
	v_mfma_f32_16x16x32_bf16 v[12:15], v[176:179], v[224:227], v[12:15]
	v_mfma_f32_16x16x32_bf16 v[56:59], v[180:183], v[196:199], v[56:59]
	v_mfma_f32_16x16x32_bf16 v[48:51], v[188:191], v[196:199], v[48:51]
	v_mfma_f32_16x16x32_bf16 v[40:43], v[180:183], v[204:207], v[40:43]
	v_mfma_f32_16x16x32_bf16 v[32:35], v[188:191], v[204:207], v[32:35]
	v_mfma_f32_16x16x32_bf16 v[24:27], v[180:183], v[212:215], v[24:27]
	v_mfma_f32_16x16x32_bf16 v[16:19], v[188:191], v[212:215], v[16:19]
	v_mfma_f32_16x16x32_bf16 v[8:11], v[180:183], v[220:223], v[8:11]
	v_mfma_f32_16x16x32_bf16 v[4:7], v[188:191], v[220:223], v[4:7]
	v_mfma_f32_16x16x32_bf16 v[56:59], v[184:187], v[200:203], v[56:59]
	v_mfma_f32_16x16x32_bf16 v[48:51], v[192:195], v[200:203], v[48:51]
	v_mfma_f32_16x16x32_bf16 v[40:43], v[184:187], v[208:211], v[40:43]
	v_mfma_f32_16x16x32_bf16 v[32:35], v[192:195], v[208:211], v[32:35]
	v_mfma_f32_16x16x32_bf16 v[24:27], v[184:187], v[216:219], v[24:27]
	v_mfma_f32_16x16x32_bf16 v[16:19], v[192:195], v[216:219], v[16:19]
	v_mfma_f32_16x16x32_bf16 v[8:11], v[184:187], v[224:227], v[8:11]
	v_mfma_f32_16x16x32_bf16 v[4:7], v[192:195], v[224:227], v[4:7]
	s_barrier
	s_setprio 0
.LBB0_342:
	s_add_i32 s50, 0, 0x10000
	s_add_i32 s33, 0, 0x14000
	ds_read_b128 v[154:157], v229
	ds_read_b128 v[168:171], v229 offset:1024
	ds_read_b128 v[172:175], v229 offset:2048
	ds_read_b128 v[176:179], v229 offset:3072
	ds_read_b128 v[180:183], v229 offset:16384
	ds_read_b128 v[184:187], v229 offset:17408
	ds_read_b128 v[188:191], v229 offset:18432
	ds_read_b128 v[192:195], v229 offset:19456
	s_add_i32 m0, s12, 0xc000
	ds_read_b128 v[196:199], v167
	ds_read_b128 v[200:203], v167 offset:1024
	ds_read_b128 v[204:207], v167 offset:2048
	ds_read_b128 v[208:211], v167 offset:3072
	ds_read_b128 v[212:215], v167 offset:4096
	ds_read_b128 v[216:219], v167 offset:5120
	ds_read_b128 v[220:223], v167 offset:6144
	ds_read_b128 v[224:227], v167 offset:7168
	global_load_lds_dwordx4 v140, s[44:45]
	s_add_i32 m0, s12, 0xe000
	s_nop 0
	global_load_lds_dwordx4 v138, s[44:45]
	s_waitcnt vmcnt(8)
	s_waitcnt lgkmcnt(0)
	s_barrier
	s_setprio 1
	v_mfma_f32_16x16x32_bf16 v[128:131], v[154:157], v[196:199], v[128:131]
	v_mfma_f32_16x16x32_bf16 v[124:127], v[172:175], v[196:199], v[124:127]
	v_mfma_f32_16x16x32_bf16 v[116:119], v[154:157], v[204:207], v[116:119]
	v_mfma_f32_16x16x32_bf16 v[108:111], v[172:175], v[204:207], v[108:111]
	v_mfma_f32_16x16x32_bf16 v[100:103], v[154:157], v[212:215], v[100:103]
	v_mfma_f32_16x16x32_bf16 v[92:95], v[172:175], v[212:215], v[92:95]
	v_mfma_f32_16x16x32_bf16 v[84:87], v[154:157], v[220:223], v[84:87]
	v_mfma_f32_16x16x32_bf16 v[76:79], v[172:175], v[220:223], v[76:79]
	v_mfma_f32_16x16x32_bf16 v[128:131], v[168:171], v[200:203], v[128:131]
	v_mfma_f32_16x16x32_bf16 v[124:127], v[176:179], v[200:203], v[124:127]
	v_mfma_f32_16x16x32_bf16 v[116:119], v[168:171], v[208:211], v[116:119]
	v_mfma_f32_16x16x32_bf16 v[108:111], v[176:179], v[208:211], v[108:111]
	v_mfma_f32_16x16x32_bf16 v[100:103], v[168:171], v[216:219], v[100:103]
	v_mfma_f32_16x16x32_bf16 v[92:95], v[176:179], v[216:219], v[92:95]
	v_mfma_f32_16x16x32_bf16 v[84:87], v[168:171], v[224:227], v[84:87]
	v_mfma_f32_16x16x32_bf16 v[76:79], v[176:179], v[224:227], v[76:79]
	v_mfma_f32_16x16x32_bf16 v[120:123], v[180:183], v[196:199], v[120:123]
	v_mfma_f32_16x16x32_bf16 v[112:115], v[188:191], v[196:199], v[112:115]
	v_mfma_f32_16x16x32_bf16 v[104:107], v[180:183], v[204:207], v[104:107]
	v_mfma_f32_16x16x32_bf16 v[96:99], v[188:191], v[204:207], v[96:99]
	v_mfma_f32_16x16x32_bf16 v[88:91], v[180:183], v[212:215], v[88:91]
	v_mfma_f32_16x16x32_bf16 v[80:83], v[188:191], v[212:215], v[80:83]
	v_mfma_f32_16x16x32_bf16 v[72:75], v[180:183], v[220:223], v[72:75]
	v_mfma_f32_16x16x32_bf16 v[68:71], v[188:191], v[220:223], v[68:71]
	v_mfma_f32_16x16x32_bf16 v[120:123], v[184:187], v[200:203], v[120:123]
	v_mfma_f32_16x16x32_bf16 v[112:115], v[192:195], v[200:203], v[112:115]
	v_mfma_f32_16x16x32_bf16 v[104:107], v[184:187], v[208:211], v[104:107]
	v_mfma_f32_16x16x32_bf16 v[96:99], v[192:195], v[208:211], v[96:99]
	v_mfma_f32_16x16x32_bf16 v[88:91], v[184:187], v[216:219], v[88:91]
	v_mfma_f32_16x16x32_bf16 v[80:83], v[192:195], v[216:219], v[80:83]
	v_mfma_f32_16x16x32_bf16 v[72:75], v[184:187], v[224:227], v[72:75]
	v_mfma_f32_16x16x32_bf16 v[68:71], v[192:195], v[224:227], v[68:71]
	s_barrier
	s_setprio 0
	s_add_i32 s43, s50, s10
	s_mov_b32 m0, s43
	ds_read_b128 v[196:199], v167 offset:16384
	ds_read_b128 v[200:203], v167 offset:17408
	ds_read_b128 v[204:207], v167 offset:18432
	ds_read_b128 v[208:211], v167 offset:19456
	ds_read_b128 v[212:215], v167 offset:20480
	ds_read_b128 v[216:219], v167 offset:21504
	ds_read_b128 v[220:223], v167 offset:22528
	ds_read_b128 v[224:227], v167 offset:23552
	global_load_lds_dwordx4 v2, s[46:47]
	s_add_i32 m0, s43, 0x2000
	s_add_u32 s50, s46, 0x80000
	s_addc_u32 s51, s47, 0
	s_add_i32 s33, s33, s10
	global_load_lds_dwordx4 v0, s[46:47]
	s_mov_b32 m0, s33
	s_nop 0
	global_load_lds_dwordx4 v2, s[50:51]
	s_add_i32 m0, s33, 0x2000
	s_nop 0
	global_load_lds_dwordx4 v0, s[50:51]
	s_mov_b32 m0, s12
	s_nop 0
	global_load_lds_dwordx4 v134, s[48:49]
	s_mov_b32 m0, s13
	s_nop 0
	global_load_lds_dwordx4 v132, s[48:49]
	s_waitcnt vmcnt(8)
	s_waitcnt lgkmcnt(0)
	s_barrier
	s_setprio 1
	v_mfma_f32_16x16x32_bf16 v[64:67], v[154:157], v[196:199], v[64:67]
	v_mfma_f32_16x16x32_bf16 v[60:63], v[172:175], v[196:199], v[60:63]
	v_mfma_f32_16x16x32_bf16 v[52:55], v[154:157], v[204:207], v[52:55]
	v_mfma_f32_16x16x32_bf16 v[44:47], v[172:175], v[204:207], v[44:47]
	v_mfma_f32_16x16x32_bf16 v[36:39], v[154:157], v[212:215], v[36:39]
	v_mfma_f32_16x16x32_bf16 v[28:31], v[172:175], v[212:215], v[28:31]
	v_mfma_f32_16x16x32_bf16 v[20:23], v[154:157], v[220:223], v[20:23]
	v_mfma_f32_16x16x32_bf16 v[12:15], v[172:175], v[220:223], v[12:15]
	v_mfma_f32_16x16x32_bf16 v[64:67], v[168:171], v[200:203], v[64:67]
	v_mfma_f32_16x16x32_bf16 v[60:63], v[176:179], v[200:203], v[60:63]
	v_mfma_f32_16x16x32_bf16 v[52:55], v[168:171], v[208:211], v[52:55]
	v_mfma_f32_16x16x32_bf16 v[44:47], v[176:179], v[208:211], v[44:47]
	v_mfma_f32_16x16x32_bf16 v[36:39], v[168:171], v[216:219], v[36:39]
	v_mfma_f32_16x16x32_bf16 v[28:31], v[176:179], v[216:219], v[28:31]
	v_mfma_f32_16x16x32_bf16 v[20:23], v[168:171], v[224:227], v[20:23]
	v_mfma_f32_16x16x32_bf16 v[12:15], v[176:179], v[224:227], v[12:15]
	v_mfma_f32_16x16x32_bf16 v[56:59], v[180:183], v[196:199], v[56:59]
	v_mfma_f32_16x16x32_bf16 v[48:51], v[188:191], v[196:199], v[48:51]
	v_mfma_f32_16x16x32_bf16 v[40:43], v[180:183], v[204:207], v[40:43]
	v_mfma_f32_16x16x32_bf16 v[32:35], v[188:191], v[204:207], v[32:35]
	v_mfma_f32_16x16x32_bf16 v[24:27], v[180:183], v[212:215], v[24:27]
	v_mfma_f32_16x16x32_bf16 v[16:19], v[188:191], v[212:215], v[16:19]
	v_mfma_f32_16x16x32_bf16 v[8:11], v[180:183], v[220:223], v[8:11]
	v_mfma_f32_16x16x32_bf16 v[4:7], v[188:191], v[220:223], v[4:7]
	v_mfma_f32_16x16x32_bf16 v[56:59], v[184:187], v[200:203], v[56:59]
	v_mfma_f32_16x16x32_bf16 v[48:51], v[192:195], v[200:203], v[48:51]
	v_mfma_f32_16x16x32_bf16 v[40:43], v[184:187], v[208:211], v[40:43]
	v_mfma_f32_16x16x32_bf16 v[32:35], v[192:195], v[208:211], v[32:35]
	v_mfma_f32_16x16x32_bf16 v[24:27], v[184:187], v[216:219], v[24:27]
	v_mfma_f32_16x16x32_bf16 v[16:19], v[192:195], v[216:219], v[16:19]
	v_mfma_f32_16x16x32_bf16 v[8:11], v[184:187], v[224:227], v[8:11]
	v_mfma_f32_16x16x32_bf16 v[4:7], v[192:195], v[224:227], v[4:7]
	s_barrier
	s_setprio 0
	s_add_i32 s33, 0, 0x18000
	s_add_i32 s43, 0, 0x1c000
	ds_read_b128 v[154:157], v229 offset:32768
	ds_read_b128 v[168:171], v229 offset:33792
	ds_read_b128 v[172:175], v229 offset:34816
	ds_read_b128 v[176:179], v229 offset:35840
	ds_read_b128 v[180:183], v229 offset:49152
	ds_read_b128 v[184:187], v229 offset:50176
	ds_read_b128 v[188:191], v229 offset:51200
	ds_read_b128 v[192:195], v229 offset:52224
	s_add_u32 s48, s48, 0x80000
	s_addc_u32 s49, s49, 0
	s_mov_b32 m0, s14
	ds_read_b128 v[196:199], v167 offset:32768
	ds_read_b128 v[200:203], v167 offset:33792
	ds_read_b128 v[204:207], v167 offset:34816
	ds_read_b128 v[208:211], v167 offset:35840
	ds_read_b128 v[212:215], v167 offset:36864
	ds_read_b128 v[216:219], v167 offset:37888
	ds_read_b128 v[220:223], v167 offset:38912
	ds_read_b128 v[224:227], v167 offset:39936
	global_load_lds_dwordx4 v134, s[48:49]
	s_mov_b32 m0, s15
	s_nop 0
	global_load_lds_dwordx4 v132, s[48:49]
	s_waitcnt vmcnt(8)
	s_waitcnt lgkmcnt(0)
	s_barrier
	s_setprio 1
	v_mfma_f32_16x16x32_bf16 v[128:131], v[154:157], v[196:199], v[128:131]
	v_mfma_f32_16x16x32_bf16 v[124:127], v[172:175], v[196:199], v[124:127]
	v_mfma_f32_16x16x32_bf16 v[116:119], v[154:157], v[204:207], v[116:119]
	v_mfma_f32_16x16x32_bf16 v[108:111], v[172:175], v[204:207], v[108:111]
	v_mfma_f32_16x16x32_bf16 v[100:103], v[154:157], v[212:215], v[100:103]
	v_mfma_f32_16x16x32_bf16 v[92:95], v[172:175], v[212:215], v[92:95]
	v_mfma_f32_16x16x32_bf16 v[84:87], v[154:157], v[220:223], v[84:87]
	v_mfma_f32_16x16x32_bf16 v[76:79], v[172:175], v[220:223], v[76:79]
	v_mfma_f32_16x16x32_bf16 v[128:131], v[168:171], v[200:203], v[128:131]
	v_mfma_f32_16x16x32_bf16 v[124:127], v[176:179], v[200:203], v[124:127]
	v_mfma_f32_16x16x32_bf16 v[116:119], v[168:171], v[208:211], v[116:119]
	v_mfma_f32_16x16x32_bf16 v[108:111], v[176:179], v[208:211], v[108:111]
	v_mfma_f32_16x16x32_bf16 v[100:103], v[168:171], v[216:219], v[100:103]
	v_mfma_f32_16x16x32_bf16 v[92:95], v[176:179], v[216:219], v[92:95]
	v_mfma_f32_16x16x32_bf16 v[84:87], v[168:171], v[224:227], v[84:87]
	v_mfma_f32_16x16x32_bf16 v[76:79], v[176:179], v[224:227], v[76:79]
	v_mfma_f32_16x16x32_bf16 v[120:123], v[180:183], v[196:199], v[120:123]
	v_mfma_f32_16x16x32_bf16 v[112:115], v[188:191], v[196:199], v[112:115]
	v_mfma_f32_16x16x32_bf16 v[104:107], v[180:183], v[204:207], v[104:107]
	v_mfma_f32_16x16x32_bf16 v[96:99], v[188:191], v[204:207], v[96:99]
	v_mfma_f32_16x16x32_bf16 v[88:91], v[180:183], v[212:215], v[88:91]
	v_mfma_f32_16x16x32_bf16 v[80:83], v[188:191], v[212:215], v[80:83]
	v_mfma_f32_16x16x32_bf16 v[72:75], v[180:183], v[220:223], v[72:75]
	v_mfma_f32_16x16x32_bf16 v[68:71], v[188:191], v[220:223], v[68:71]
	v_mfma_f32_16x16x32_bf16 v[120:123], v[184:187], v[200:203], v[120:123]
	v_mfma_f32_16x16x32_bf16 v[112:115], v[192:195], v[200:203], v[112:115]
	v_mfma_f32_16x16x32_bf16 v[104:107], v[184:187], v[208:211], v[104:107]
	v_mfma_f32_16x16x32_bf16 v[96:99], v[192:195], v[208:211], v[96:99]
	v_mfma_f32_16x16x32_bf16 v[88:91], v[184:187], v[216:219], v[88:91]
	v_mfma_f32_16x16x32_bf16 v[80:83], v[192:195], v[216:219], v[80:83]
	v_mfma_f32_16x16x32_bf16 v[72:75], v[184:187], v[224:227], v[72:75]
	v_mfma_f32_16x16x32_bf16 v[68:71], v[192:195], v[224:227], v[68:71]
	s_barrier
	s_setprio 0
	s_add_i32 s33, s33, s10
	s_mov_b32 m0, s33
	ds_read_b128 v[196:199], v167 offset:49152
	ds_read_b128 v[200:203], v167 offset:50176
	ds_read_b128 v[204:207], v167 offset:51200
	ds_read_b128 v[208:211], v167 offset:52224
	ds_read_b128 v[212:215], v167 offset:53248
	ds_read_b128 v[216:219], v167 offset:54272
	ds_read_b128 v[220:223], v167 offset:55296
	ds_read_b128 v[224:227], v167 offset:56320
	s_add_u32 s100, s46, 0x80
	s_addc_u32 s101, s47, 0
	global_load_lds_dwordx4 v2, s[100:101]
	s_add_i32 m0, s33, 0x2000
	s_add_u32 s46, s46, 0x80080
	s_addc_u32 s47, s47, 0
	s_add_i32 s33, s43, s10
	s_add_u32 s100, s46, 0xfff80000
	s_addc_u32 s101, s47, -1
	global_load_lds_dwordx4 v0, s[100:101]
	s_mov_b32 m0, s33
	s_nop 0
	global_load_lds_dwordx4 v2, s[46:47]
	s_add_i32 m0, s33, 0x2000
	s_nop 0
	global_load_lds_dwordx4 v0, s[46:47]
	s_mov_b32 m0, s16
	s_nop 0
	s_add_u32 s100, s48, 0xfff80080
	s_addc_u32 s101, s49, -1
	global_load_lds_dwordx4 v134, s[100:101]
	s_mov_b32 m0, s17
	s_nop 0
	s_add_u32 s100, s48, 0xfff80080
	s_addc_u32 s101, s49, -1
	global_load_lds_dwordx4 v132, s[100:101]
	s_add_i32 s35, s35, 2
	s_add_u32 s31, s31, 0x100
	s_addc_u32 s34, s34, 0
	s_add_u32 s44, s44, 0x100
	s_addc_u32 s45, s45, 0
	s_add_u32 s33, s44, 0xfff80080
	s_addc_u32 s43, s45, -1
	s_cmp_eq_u32 s35, 28
	s_cselect_b32 s49, s27, s43
	s_cselect_b32 s48, s28, s33
	s_cselect_b32 s47, s25, s34
	s_cselect_b32 s46, s29, s31
	s_cmp_gt_u32 s35, 29
	s_waitcnt vmcnt(8)
	s_waitcnt lgkmcnt(0)
	s_barrier
	s_setprio 1
	v_mfma_f32_16x16x32_bf16 v[64:67], v[154:157], v[196:199], v[64:67]
	v_mfma_f32_16x16x32_bf16 v[60:63], v[172:175], v[196:199], v[60:63]
	v_mfma_f32_16x16x32_bf16 v[52:55], v[154:157], v[204:207], v[52:55]
	v_mfma_f32_16x16x32_bf16 v[44:47], v[172:175], v[204:207], v[44:47]
	v_mfma_f32_16x16x32_bf16 v[36:39], v[154:157], v[212:215], v[36:39]
	v_mfma_f32_16x16x32_bf16 v[28:31], v[172:175], v[212:215], v[28:31]
	v_mfma_f32_16x16x32_bf16 v[20:23], v[154:157], v[220:223], v[20:23]
	v_mfma_f32_16x16x32_bf16 v[12:15], v[172:175], v[220:223], v[12:15]
	v_mfma_f32_16x16x32_bf16 v[64:67], v[168:171], v[200:203], v[64:67]
	v_mfma_f32_16x16x32_bf16 v[60:63], v[176:179], v[200:203], v[60:63]
	v_mfma_f32_16x16x32_bf16 v[52:55], v[168:171], v[208:211], v[52:55]
	v_mfma_f32_16x16x32_bf16 v[44:47], v[176:179], v[208:211], v[44:47]
	v_mfma_f32_16x16x32_bf16 v[36:39], v[168:171], v[216:219], v[36:39]
	v_mfma_f32_16x16x32_bf16 v[28:31], v[176:179], v[216:219], v[28:31]
	v_mfma_f32_16x16x32_bf16 v[20:23], v[168:171], v[224:227], v[20:23]
	v_mfma_f32_16x16x32_bf16 v[12:15], v[176:179], v[224:227], v[12:15]
	v_mfma_f32_16x16x32_bf16 v[56:59], v[180:183], v[196:199], v[56:59]
	v_mfma_f32_16x16x32_bf16 v[48:51], v[188:191], v[196:199], v[48:51]
	v_mfma_f32_16x16x32_bf16 v[40:43], v[180:183], v[204:207], v[40:43]
	v_mfma_f32_16x16x32_bf16 v[32:35], v[188:191], v[204:207], v[32:35]
	v_mfma_f32_16x16x32_bf16 v[24:27], v[180:183], v[212:215], v[24:27]
	v_mfma_f32_16x16x32_bf16 v[16:19], v[188:191], v[212:215], v[16:19]
	v_mfma_f32_16x16x32_bf16 v[8:11], v[180:183], v[220:223], v[8:11]
	v_mfma_f32_16x16x32_bf16 v[4:7], v[188:191], v[220:223], v[4:7]
	v_mfma_f32_16x16x32_bf16 v[56:59], v[184:187], v[200:203], v[56:59]
	v_mfma_f32_16x16x32_bf16 v[48:51], v[192:195], v[200:203], v[48:51]
	v_mfma_f32_16x16x32_bf16 v[40:43], v[184:187], v[208:211], v[40:43]
	v_mfma_f32_16x16x32_bf16 v[32:35], v[192:195], v[208:211], v[32:35]
	v_mfma_f32_16x16x32_bf16 v[24:27], v[184:187], v[216:219], v[24:27]
	v_mfma_f32_16x16x32_bf16 v[16:19], v[192:195], v[216:219], v[16:19]
	v_mfma_f32_16x16x32_bf16 v[8:11], v[184:187], v[224:227], v[8:11]
	v_mfma_f32_16x16x32_bf16 v[4:7], v[192:195], v[224:227], v[4:7]
	s_barrier
	s_setprio 0
	s_cbranch_scc0 .LBB0_342
	s_and_b64 vcc, exec, s[22:23]
	s_cbranch_vccz .LBB0_345
	s_nop 0

.Lgu_skip2_p:
	s_mov_b32 s32, 0
	s_waitcnt lgkmcnt(0)
	s_barrier
	s_setprio 1
	v_mfma_f32_16x16x32_bf16 v[64:67], v[142:145], v[184:187], 0
	v_mfma_f32_16x16x32_bf16 v[56:59], v[150:153], v[184:187], 0
	v_mfma_f32_16x16x32_bf16 v[48:51], v[142:145], v[192:195], 0
	v_mfma_f32_16x16x32_bf16 v[40:43], v[150:153], v[192:195], 0
	v_mfma_f32_16x16x32_bf16 v[32:35], v[142:145], v[200:203], 0
	v_mfma_f32_16x16x32_bf16 v[24:27], v[150:153], v[200:203], 0
	v_mfma_f32_16x16x32_bf16 v[16:19], v[142:145], v[208:211], 0
	v_mfma_f32_16x16x32_bf16 v[8:11], v[150:153], v[208:211], 0
	v_mfma_f32_16x16x32_bf16 v[64:67], v[146:149], v[188:191], v[64:67]
	v_mfma_f32_16x16x32_bf16 v[56:59], v[154:157], v[188:191], v[56:59]
	v_mfma_f32_16x16x32_bf16 v[48:51], v[146:149], v[196:199], v[48:51]
	v_mfma_f32_16x16x32_bf16 v[40:43], v[154:157], v[196:199], v[40:43]
	v_mfma_f32_16x16x32_bf16 v[32:35], v[146:149], v[204:207], v[32:35]
	v_mfma_f32_16x16x32_bf16 v[24:27], v[154:157], v[204:207], v[24:27]
	v_mfma_f32_16x16x32_bf16 v[16:19], v[146:149], v[212:215], v[16:19]
	v_mfma_f32_16x16x32_bf16 v[8:11], v[154:157], v[212:215], v[8:11]
	v_mfma_f32_16x16x32_bf16 v[60:63], v[168:171], v[184:187], 0
	v_mfma_f32_16x16x32_bf16 v[52:55], v[176:179], v[184:187], 0
	v_mfma_f32_16x16x32_bf16 v[44:47], v[168:171], v[192:195], 0
	v_mfma_f32_16x16x32_bf16 v[36:39], v[176:179], v[192:195], 0
	v_mfma_f32_16x16x32_bf16 v[28:31], v[168:171], v[200:203], 0
	v_mfma_f32_16x16x32_bf16 v[20:23], v[176:179], v[200:203], 0
	v_mfma_f32_16x16x32_bf16 v[12:15], v[168:171], v[208:211], 0
	v_mfma_f32_16x16x32_bf16 v[4:7], v[176:179], v[208:211], 0
	v_mfma_f32_16x16x32_bf16 v[60:63], v[172:175], v[188:191], v[60:63]
	v_mfma_f32_16x16x32_bf16 v[52:55], v[180:183], v[188:191], v[52:55]
	v_mfma_f32_16x16x32_bf16 v[44:47], v[172:175], v[196:199], v[44:47]
	v_mfma_f32_16x16x32_bf16 v[36:39], v[180:183], v[196:199], v[36:39]
	v_mfma_f32_16x16x32_bf16 v[28:31], v[172:175], v[204:207], v[28:31]
	v_mfma_f32_16x16x32_bf16 v[20:23], v[180:183], v[204:207], v[20:23]
	v_mfma_f32_16x16x32_bf16 v[12:15], v[172:175], v[212:215], v[12:15]
	v_mfma_f32_16x16x32_bf16 v[4:7], v[180:183], v[212:215], v[4:7]
	s_barrier
	s_setprio 0
	s_add_i32 s14, 0, 0x18000
	s_add_i32 s15, 0, 0x1c000
	ds_read_b128 v[142:145], v133 offset:32768
	ds_read_b128 v[146:149], v133 offset:33792
	ds_read_b128 v[150:153], v133 offset:34816
	ds_read_b128 v[154:157], v133 offset:35840
	ds_read_b128 v[168:171], v133 offset:49152
	ds_read_b128 v[172:175], v133 offset:50176
	ds_read_b128 v[176:179], v133 offset:51200
	ds_read_b128 v[180:183], v133 offset:52224
	s_add_u32 s12, s48, 0x80000
	s_addc_u32 s13, s49, 0
	s_mov_b32 m0, s62
	ds_read_b128 v[184:187], v167 offset:32768
	ds_read_b128 v[188:191], v167 offset:33792
	ds_read_b128 v[192:195], v167 offset:34816
	ds_read_b128 v[196:199], v167 offset:35840
	ds_read_b128 v[200:203], v167 offset:36864
	ds_read_b128 v[204:207], v167 offset:37888
	ds_read_b128 v[208:211], v167 offset:38912
	ds_read_b128 v[212:215], v167 offset:39936
	global_load_lds_dwordx4 v134, s[12:13]
	s_mov_b32 m0, s63
	s_nop 0
	global_load_lds_dwordx4 v132, s[12:13]
	s_waitcnt vmcnt(8)
	s_waitcnt lgkmcnt(0)
	s_barrier
	s_setprio 1
	v_mfma_f32_16x16x32_bf16 v[124:127], v[142:145], v[184:187], v[124:127]
	v_mfma_f32_16x16x32_bf16 v[120:123], v[150:153], v[184:187], v[120:123]
	v_mfma_f32_16x16x32_bf16 v[112:115], v[142:145], v[192:195], v[112:115]
	v_mfma_f32_16x16x32_bf16 v[104:107], v[150:153], v[192:195], v[104:107]
	v_mfma_f32_16x16x32_bf16 v[96:99], v[142:145], v[200:203], v[96:99]
	v_mfma_f32_16x16x32_bf16 v[88:91], v[150:153], v[200:203], v[88:91]
	v_mfma_f32_16x16x32_bf16 v[80:83], v[142:145], v[208:211], v[80:83]
	v_mfma_f32_16x16x32_bf16 v[72:75], v[150:153], v[208:211], v[72:75]
	v_mfma_f32_16x16x32_bf16 v[124:127], v[146:149], v[188:191], v[124:127]
	v_mfma_f32_16x16x32_bf16 v[120:123], v[154:157], v[188:191], v[120:123]
	v_mfma_f32_16x16x32_bf16 v[112:115], v[146:149], v[196:199], v[112:115]
	v_mfma_f32_16x16x32_bf16 v[104:107], v[154:157], v[196:199], v[104:107]
	v_mfma_f32_16x16x32_bf16 v[96:99], v[146:149], v[204:207], v[96:99]
	v_mfma_f32_16x16x32_bf16 v[88:91], v[154:157], v[204:207], v[88:91]
	v_mfma_f32_16x16x32_bf16 v[80:83], v[146:149], v[212:215], v[80:83]
	v_mfma_f32_16x16x32_bf16 v[72:75], v[154:157], v[212:215], v[72:75]
	v_mfma_f32_16x16x32_bf16 v[128:131], v[168:171], v[184:187], v[128:131]
	v_mfma_f32_16x16x32_bf16 v[116:119], v[176:179], v[184:187], v[116:119]
	v_mfma_f32_16x16x32_bf16 v[108:111], v[168:171], v[192:195], v[108:111]
	v_mfma_f32_16x16x32_bf16 v[100:103], v[176:179], v[192:195], v[100:103]
	v_mfma_f32_16x16x32_bf16 v[92:95], v[168:171], v[200:203], v[92:95]
	v_mfma_f32_16x16x32_bf16 v[84:87], v[176:179], v[200:203], v[84:87]
	v_mfma_f32_16x16x32_bf16 v[76:79], v[168:171], v[208:211], v[76:79]
	v_mfma_f32_16x16x32_bf16 v[68:71], v[176:179], v[208:211], v[68:71]
	v_mfma_f32_16x16x32_bf16 v[128:131], v[172:175], v[188:191], v[128:131]
	v_mfma_f32_16x16x32_bf16 v[116:119], v[180:183], v[188:191], v[116:119]
	v_mfma_f32_16x16x32_bf16 v[108:111], v[172:175], v[196:199], v[108:111]
	v_mfma_f32_16x16x32_bf16 v[100:103], v[180:183], v[196:199], v[100:103]
	v_mfma_f32_16x16x32_bf16 v[92:95], v[172:175], v[204:207], v[92:95]
	v_mfma_f32_16x16x32_bf16 v[84:87], v[180:183], v[204:207], v[84:87]
	v_mfma_f32_16x16x32_bf16 v[76:79], v[172:175], v[212:215], v[76:79]
	v_mfma_f32_16x16x32_bf16 v[68:71], v[180:183], v[212:215], v[68:71]
	s_barrier
	s_setprio 0
	s_add_i32 s12, s14, s56
	s_mov_b32 m0, s12
	ds_read_b128 v[184:187], v167 offset:49152
	ds_read_b128 v[188:191], v167 offset:50176
	ds_read_b128 v[192:195], v167 offset:51200
	ds_read_b128 v[196:199], v167 offset:52224
	ds_read_b128 v[200:203], v167 offset:53248
	ds_read_b128 v[204:207], v167 offset:54272
	ds_read_b128 v[208:211], v167 offset:55296
	ds_read_b128 v[212:215], v167 offset:56320
	s_add_u32 s100, s46, 0x80
	s_addc_u32 s101, s47, 0
	global_load_lds_dwordx4 v2, s[100:101]
	s_add_i32 m0, s12, 0x2000
	s_add_u32 s12, s46, 0x80080
	s_addc_u32 s13, s47, 0
	s_add_i32 s14, s15, s56
	s_add_u32 s100, s46, 0x80
	s_addc_u32 s101, s47, 0
	global_load_lds_dwordx4 v0, s[100:101]
	s_mov_b32 m0, s14
	s_nop 0
	global_load_lds_dwordx4 v2, s[12:13]
	s_add_i32 m0, s14, 0x2000
	s_nop 0
	global_load_lds_dwordx4 v0, s[12:13]
	s_mov_b32 m0, s64
	s_nop 0
	s_add_u32 s100, s48, 0x80
	s_addc_u32 s101, s49, 0
	global_load_lds_dwordx4 v134, s[100:101]
	s_mov_b32 m0, s65
	s_nop 0
	s_add_u32 s100, s48, 0x80
	s_addc_u32 s101, s49, 0
	global_load_lds_dwordx4 v132, s[100:101]
	s_add_i32 s11, s11, 2
	s_add_u32 s9, s9, 0x100
	s_addc_u32 s10, s10, 0
	s_add_u32 s44, s44, 0x100
	s_addc_u32 s45, s45, 0
	s_add_u32 s12, s44, 0xfff80080
	s_addc_u32 s13, s45, -1
	s_cmp_eq_u32 s11, 28
	s_cselect_b32 s49, s5, s13
	s_cselect_b32 s48, s6, s12
	s_cselect_b32 s47, s7, s10
	s_cselect_b32 s46, s8, s9
	s_waitcnt vmcnt(8)
	s_waitcnt lgkmcnt(0)
	s_barrier
	s_setprio 1
	v_mfma_f32_16x16x32_bf16 v[64:67], v[142:145], v[184:187], v[64:67]
	v_mfma_f32_16x16x32_bf16 v[56:59], v[150:153], v[184:187], v[56:59]
	v_mfma_f32_16x16x32_bf16 v[48:51], v[142:145], v[192:195], v[48:51]
	v_mfma_f32_16x16x32_bf16 v[40:43], v[150:153], v[192:195], v[40:43]
	v_mfma_f32_16x16x32_bf16 v[32:35], v[142:145], v[200:203], v[32:35]
	v_mfma_f32_16x16x32_bf16 v[24:27], v[150:153], v[200:203], v[24:27]
	v_mfma_f32_16x16x32_bf16 v[16:19], v[142:145], v[208:211], v[16:19]
	v_mfma_f32_16x16x32_bf16 v[8:11], v[150:153], v[208:211], v[8:11]
	v_mfma_f32_16x16x32_bf16 v[64:67], v[146:149], v[188:191], v[64:67]
	v_mfma_f32_16x16x32_bf16 v[56:59], v[154:157], v[188:191], v[56:59]
	v_mfma_f32_16x16x32_bf16 v[48:51], v[146:149], v[196:199], v[48:51]
	v_mfma_f32_16x16x32_bf16 v[40:43], v[154:157], v[196:199], v[40:43]
	v_mfma_f32_16x16x32_bf16 v[32:35], v[146:149], v[204:207], v[32:35]
	v_mfma_f32_16x16x32_bf16 v[24:27], v[154:157], v[204:207], v[24:27]
	v_mfma_f32_16x16x32_bf16 v[16:19], v[146:149], v[212:215], v[16:19]
	v_mfma_f32_16x16x32_bf16 v[8:11], v[154:157], v[212:215], v[8:11]
	v_mfma_f32_16x16x32_bf16 v[60:63], v[168:171], v[184:187], v[60:63]
	v_mfma_f32_16x16x32_bf16 v[52:55], v[176:179], v[184:187], v[52:55]
	v_mfma_f32_16x16x32_bf16 v[44:47], v[168:171], v[192:195], v[44:47]
	v_mfma_f32_16x16x32_bf16 v[36:39], v[176:179], v[192:195], v[36:39]
	v_mfma_f32_16x16x32_bf16 v[28:31], v[168:171], v[200:203], v[28:31]
	v_mfma_f32_16x16x32_bf16 v[20:23], v[176:179], v[200:203], v[20:23]
	v_mfma_f32_16x16x32_bf16 v[12:15], v[168:171], v[208:211], v[12:15]
	v_mfma_f32_16x16x32_bf16 v[4:7], v[176:179], v[208:211], v[4:7]
	v_mfma_f32_16x16x32_bf16 v[60:63], v[172:175], v[188:191], v[60:63]
	v_mfma_f32_16x16x32_bf16 v[52:55], v[180:183], v[188:191], v[52:55]
	v_mfma_f32_16x16x32_bf16 v[44:47], v[172:175], v[196:199], v[44:47]
	v_mfma_f32_16x16x32_bf16 v[36:39], v[180:183], v[196:199], v[36:39]
	v_mfma_f32_16x16x32_bf16 v[28:31], v[172:175], v[204:207], v[28:31]
	v_mfma_f32_16x16x32_bf16 v[20:23], v[180:183], v[204:207], v[20:23]
	v_mfma_f32_16x16x32_bf16 v[12:15], v[172:175], v[212:215], v[12:15]
	v_mfma_f32_16x16x32_bf16 v[4:7], v[180:183], v[212:215], v[4:7]
	s_barrier
	s_setprio 0
.LBB0_1066:
	s_add_i32 s14, 0, 0x10000
	s_add_i32 s15, 0, 0x14000
	ds_read_b128 v[142:145], v133
	ds_read_b128 v[146:149], v133 offset:1024
	ds_read_b128 v[150:153], v133 offset:2048
	ds_read_b128 v[154:157], v133 offset:3072
	ds_read_b128 v[168:171], v133 offset:16384
	ds_read_b128 v[172:175], v133 offset:17408
	ds_read_b128 v[176:179], v133 offset:18432
	ds_read_b128 v[180:183], v133 offset:19456
	s_add_i32 m0, s60, 0xc000
	ds_read_b128 v[184:187], v167
	ds_read_b128 v[188:191], v167 offset:1024
	ds_read_b128 v[192:195], v167 offset:2048
	ds_read_b128 v[196:199], v167 offset:3072
	ds_read_b128 v[200:203], v167 offset:4096
	ds_read_b128 v[204:207], v167 offset:5120
	ds_read_b128 v[208:211], v167 offset:6144
	ds_read_b128 v[212:215], v167 offset:7168
	global_load_lds_dwordx4 v140, s[44:45]
	s_add_i32 m0, s60, 0xe000
	s_nop 0
	global_load_lds_dwordx4 v138, s[44:45]
	s_waitcnt vmcnt(8)
	s_waitcnt lgkmcnt(0)
	s_barrier
	s_setprio 1
	v_mfma_f32_16x16x32_bf16 v[124:127], v[142:145], v[184:187], v[124:127]
	v_mfma_f32_16x16x32_bf16 v[120:123], v[150:153], v[184:187], v[120:123]
	v_mfma_f32_16x16x32_bf16 v[112:115], v[142:145], v[192:195], v[112:115]
	v_mfma_f32_16x16x32_bf16 v[104:107], v[150:153], v[192:195], v[104:107]
	v_mfma_f32_16x16x32_bf16 v[96:99], v[142:145], v[200:203], v[96:99]
	v_mfma_f32_16x16x32_bf16 v[88:91], v[150:153], v[200:203], v[88:91]
	v_mfma_f32_16x16x32_bf16 v[80:83], v[142:145], v[208:211], v[80:83]
	v_mfma_f32_16x16x32_bf16 v[72:75], v[150:153], v[208:211], v[72:75]
	v_mfma_f32_16x16x32_bf16 v[124:127], v[146:149], v[188:191], v[124:127]
	v_mfma_f32_16x16x32_bf16 v[120:123], v[154:157], v[188:191], v[120:123]
	v_mfma_f32_16x16x32_bf16 v[112:115], v[146:149], v[196:199], v[112:115]
	v_mfma_f32_16x16x32_bf16 v[104:107], v[154:157], v[196:199], v[104:107]
	v_mfma_f32_16x16x32_bf16 v[96:99], v[146:149], v[204:207], v[96:99]
	v_mfma_f32_16x16x32_bf16 v[88:91], v[154:157], v[204:207], v[88:91]
	v_mfma_f32_16x16x32_bf16 v[80:83], v[146:149], v[212:215], v[80:83]
	v_mfma_f32_16x16x32_bf16 v[72:75], v[154:157], v[212:215], v[72:75]
	v_mfma_f32_16x16x32_bf16 v[128:131], v[168:171], v[184:187], v[128:131]
	v_mfma_f32_16x16x32_bf16 v[116:119], v[176:179], v[184:187], v[116:119]
	v_mfma_f32_16x16x32_bf16 v[108:111], v[168:171], v[192:195], v[108:111]
	v_mfma_f32_16x16x32_bf16 v[100:103], v[176:179], v[192:195], v[100:103]
	v_mfma_f32_16x16x32_bf16 v[92:95], v[168:171], v[200:203], v[92:95]
	v_mfma_f32_16x16x32_bf16 v[84:87], v[176:179], v[200:203], v[84:87]
	v_mfma_f32_16x16x32_bf16 v[76:79], v[168:171], v[208:211], v[76:79]
	v_mfma_f32_16x16x32_bf16 v[68:71], v[176:179], v[208:211], v[68:71]
	v_mfma_f32_16x16x32_bf16 v[128:131], v[172:175], v[188:191], v[128:131]
	v_mfma_f32_16x16x32_bf16 v[116:119], v[180:183], v[188:191], v[116:119]
	v_mfma_f32_16x16x32_bf16 v[108:111], v[172:175], v[196:199], v[108:111]
	v_mfma_f32_16x16x32_bf16 v[100:103], v[180:183], v[196:199], v[100:103]
	v_mfma_f32_16x16x32_bf16 v[92:95], v[172:175], v[204:207], v[92:95]
	v_mfma_f32_16x16x32_bf16 v[84:87], v[180:183], v[204:207], v[84:87]
	v_mfma_f32_16x16x32_bf16 v[76:79], v[172:175], v[212:215], v[76:79]
	v_mfma_f32_16x16x32_bf16 v[68:71], v[180:183], v[212:215], v[68:71]
	s_barrier
	s_setprio 0
	s_add_i32 s12, s14, s56
	s_mov_b32 m0, s12
	ds_read_b128 v[184:187], v167 offset:16384
	ds_read_b128 v[188:191], v167 offset:17408
	ds_read_b128 v[192:195], v167 offset:18432
	ds_read_b128 v[196:199], v167 offset:19456
	ds_read_b128 v[200:203], v167 offset:20480
	ds_read_b128 v[204:207], v167 offset:21504
	ds_read_b128 v[208:211], v167 offset:22528
	ds_read_b128 v[212:215], v167 offset:23552
	global_load_lds_dwordx4 v2, s[46:47]
	s_add_i32 m0, s12, 0x2000
	s_add_u32 s12, s46, 0x80000
	s_addc_u32 s13, s47, 0
	s_add_i32 s14, s15, s56
	global_load_lds_dwordx4 v0, s[46:47]
	s_mov_b32 m0, s14
	s_nop 0
	global_load_lds_dwordx4 v2, s[12:13]
	s_add_i32 m0, s14, 0x2000
	s_nop 0
	global_load_lds_dwordx4 v0, s[12:13]
	s_mov_b32 m0, s60
	s_nop 0
	global_load_lds_dwordx4 v134, s[48:49]
	s_mov_b32 m0, s61
	s_nop 0
	global_load_lds_dwordx4 v132, s[48:49]
	s_waitcnt vmcnt(8)
	s_waitcnt lgkmcnt(0)
	s_barrier
	s_setprio 1
	v_mfma_f32_16x16x32_bf16 v[64:67], v[142:145], v[184:187], v[64:67]
	v_mfma_f32_16x16x32_bf16 v[56:59], v[150:153], v[184:187], v[56:59]
	v_mfma_f32_16x16x32_bf16 v[48:51], v[142:145], v[192:195], v[48:51]
	v_mfma_f32_16x16x32_bf16 v[40:43], v[150:153], v[192:195], v[40:43]
	v_mfma_f32_16x16x32_bf16 v[32:35], v[142:145], v[200:203], v[32:35]
	v_mfma_f32_16x16x32_bf16 v[24:27], v[150:153], v[200:203], v[24:27]
	v_mfma_f32_16x16x32_bf16 v[16:19], v[142:145], v[208:211], v[16:19]
	v_mfma_f32_16x16x32_bf16 v[8:11], v[150:153], v[208:211], v[8:11]
	v_mfma_f32_16x16x32_bf16 v[64:67], v[146:149], v[188:191], v[64:67]
	v_mfma_f32_16x16x32_bf16 v[56:59], v[154:157], v[188:191], v[56:59]
	v_mfma_f32_16x16x32_bf16 v[48:51], v[146:149], v[196:199], v[48:51]
	v_mfma_f32_16x16x32_bf16 v[40:43], v[154:157], v[196:199], v[40:43]
	v_mfma_f32_16x16x32_bf16 v[32:35], v[146:149], v[204:207], v[32:35]
	v_mfma_f32_16x16x32_bf16 v[24:27], v[154:157], v[204:207], v[24:27]
	v_mfma_f32_16x16x32_bf16 v[16:19], v[146:149], v[212:215], v[16:19]
	v_mfma_f32_16x16x32_bf16 v[8:11], v[154:157], v[212:215], v[8:11]
	v_mfma_f32_16x16x32_bf16 v[60:63], v[168:171], v[184:187], v[60:63]
	v_mfma_f32_16x16x32_bf16 v[52:55], v[176:179], v[184:187], v[52:55]
	v_mfma_f32_16x16x32_bf16 v[44:47], v[168:171], v[192:195], v[44:47]
	v_mfma_f32_16x16x32_bf16 v[36:39], v[176:179], v[192:195], v[36:39]
	v_mfma_f32_16x16x32_bf16 v[28:31], v[168:171], v[200:203], v[28:31]
	v_mfma_f32_16x16x32_bf16 v[20:23], v[176:179], v[200:203], v[20:23]
	v_mfma_f32_16x16x32_bf16 v[12:15], v[168:171], v[208:211], v[12:15]
	v_mfma_f32_16x16x32_bf16 v[4:7], v[176:179], v[208:211], v[4:7]
	v_mfma_f32_16x16x32_bf16 v[60:63], v[172:175], v[188:191], v[60:63]
	v_mfma_f32_16x16x32_bf16 v[52:55], v[180:183], v[188:191], v[52:55]
	v_mfma_f32_16x16x32_bf16 v[44:47], v[172:175], v[196:199], v[44:47]
	v_mfma_f32_16x16x32_bf16 v[36:39], v[180:183], v[196:199], v[36:39]
	v_mfma_f32_16x16x32_bf16 v[28:31], v[172:175], v[204:207], v[28:31]
	v_mfma_f32_16x16x32_bf16 v[20:23], v[180:183], v[204:207], v[20:23]
	v_mfma_f32_16x16x32_bf16 v[12:15], v[172:175], v[212:215], v[12:15]
	v_mfma_f32_16x16x32_bf16 v[4:7], v[180:183], v[212:215], v[4:7]
	s_barrier
	s_setprio 0
	s_add_i32 s14, 0, 0x18000
	s_add_i32 s15, 0, 0x1c000
	ds_read_b128 v[142:145], v133 offset:32768
	ds_read_b128 v[146:149], v133 offset:33792
	ds_read_b128 v[150:153], v133 offset:34816
	ds_read_b128 v[154:157], v133 offset:35840
	ds_read_b128 v[168:171], v133 offset:49152
	ds_read_b128 v[172:175], v133 offset:50176
	ds_read_b128 v[176:179], v133 offset:51200
	ds_read_b128 v[180:183], v133 offset:52224
	s_add_u32 s12, s48, 0x80000
	s_addc_u32 s13, s49, 0
	s_mov_b32 m0, s62
	ds_read_b128 v[184:187], v167 offset:32768
	ds_read_b128 v[188:191], v167 offset:33792
	ds_read_b128 v[192:195], v167 offset:34816
	ds_read_b128 v[196:199], v167 offset:35840
	ds_read_b128 v[200:203], v167 offset:36864
	ds_read_b128 v[204:207], v167 offset:37888
	ds_read_b128 v[208:211], v167 offset:38912
	ds_read_b128 v[212:215], v167 offset:39936
	global_load_lds_dwordx4 v134, s[12:13]
	s_mov_b32 m0, s63
	s_nop 0
	global_load_lds_dwordx4 v132, s[12:13]
	s_waitcnt vmcnt(8)
	s_waitcnt lgkmcnt(0)
	s_barrier
	s_setprio 1
	v_mfma_f32_16x16x32_bf16 v[124:127], v[142:145], v[184:187], v[124:127]
	v_mfma_f32_16x16x32_bf16 v[120:123], v[150:153], v[184:187], v[120:123]
	v_mfma_f32_16x16x32_bf16 v[112:115], v[142:145], v[192:195], v[112:115]
	v_mfma_f32_16x16x32_bf16 v[104:107], v[150:153], v[192:195], v[104:107]
	v_mfma_f32_16x16x32_bf16 v[96:99], v[142:145], v[200:203], v[96:99]
	v_mfma_f32_16x16x32_bf16 v[88:91], v[150:153], v[200:203], v[88:91]
	v_mfma_f32_16x16x32_bf16 v[80:83], v[142:145], v[208:211], v[80:83]
	v_mfma_f32_16x16x32_bf16 v[72:75], v[150:153], v[208:211], v[72:75]
	v_mfma_f32_16x16x32_bf16 v[124:127], v[146:149], v[188:191], v[124:127]
	v_mfma_f32_16x16x32_bf16 v[120:123], v[154:157], v[188:191], v[120:123]
	v_mfma_f32_16x16x32_bf16 v[112:115], v[146:149], v[196:199], v[112:115]
	v_mfma_f32_16x16x32_bf16 v[104:107], v[154:157], v[196:199], v[104:107]
	v_mfma_f32_16x16x32_bf16 v[96:99], v[146:149], v[204:207], v[96:99]
	v_mfma_f32_16x16x32_bf16 v[88:91], v[154:157], v[204:207], v[88:91]
	v_mfma_f32_16x16x32_bf16 v[80:83], v[146:149], v[212:215], v[80:83]
	v_mfma_f32_16x16x32_bf16 v[72:75], v[154:157], v[212:215], v[72:75]
	v_mfma_f32_16x16x32_bf16 v[128:131], v[168:171], v[184:187], v[128:131]
	v_mfma_f32_16x16x32_bf16 v[116:119], v[176:179], v[184:187], v[116:119]
	v_mfma_f32_16x16x32_bf16 v[108:111], v[168:171], v[192:195], v[108:111]
	v_mfma_f32_16x16x32_bf16 v[100:103], v[176:179], v[192:195], v[100:103]
	v_mfma_f32_16x16x32_bf16 v[92:95], v[168:171], v[200:203], v[92:95]
	v_mfma_f32_16x16x32_bf16 v[84:87], v[176:179], v[200:203], v[84:87]
	v_mfma_f32_16x16x32_bf16 v[76:79], v[168:171], v[208:211], v[76:79]
	v_mfma_f32_16x16x32_bf16 v[68:71], v[176:179], v[208:211], v[68:71]
	v_mfma_f32_16x16x32_bf16 v[128:131], v[172:175], v[188:191], v[128:131]
	v_mfma_f32_16x16x32_bf16 v[116:119], v[180:183], v[188:191], v[116:119]
	v_mfma_f32_16x16x32_bf16 v[108:111], v[172:175], v[196:199], v[108:111]
	v_mfma_f32_16x16x32_bf16 v[100:103], v[180:183], v[196:199], v[100:103]
	v_mfma_f32_16x16x32_bf16 v[92:95], v[172:175], v[204:207], v[92:95]
	v_mfma_f32_16x16x32_bf16 v[84:87], v[180:183], v[204:207], v[84:87]
	v_mfma_f32_16x16x32_bf16 v[76:79], v[172:175], v[212:215], v[76:79]
	v_mfma_f32_16x16x32_bf16 v[68:71], v[180:183], v[212:215], v[68:71]
	s_barrier
	s_setprio 0
	s_add_i32 s12, s14, s56
	s_mov_b32 m0, s12
	ds_read_b128 v[184:187], v167 offset:49152
	ds_read_b128 v[188:191], v167 offset:50176
	ds_read_b128 v[192:195], v167 offset:51200
	ds_read_b128 v[196:199], v167 offset:52224
	ds_read_b128 v[200:203], v167 offset:53248
	ds_read_b128 v[204:207], v167 offset:54272
	ds_read_b128 v[208:211], v167 offset:55296
	ds_read_b128 v[212:215], v167 offset:56320
	s_add_u32 s100, s46, 0x80
	s_addc_u32 s101, s47, 0
	global_load_lds_dwordx4 v2, s[100:101]
	s_add_i32 m0, s12, 0x2000
	s_add_u32 s12, s46, 0x80080
	s_addc_u32 s13, s47, 0
	s_add_i32 s14, s15, s56
	s_add_u32 s100, s46, 0x80
	s_addc_u32 s101, s47, 0
	global_load_lds_dwordx4 v0, s[100:101]
	s_mov_b32 m0, s14
	s_nop 0
	global_load_lds_dwordx4 v2, s[12:13]
	s_add_i32 m0, s14, 0x2000
	s_nop 0
	global_load_lds_dwordx4 v0, s[12:13]
	s_mov_b32 m0, s64
	s_nop 0
	s_add_u32 s100, s48, 0x80
	s_addc_u32 s101, s49, 0
	global_load_lds_dwordx4 v134, s[100:101]
	s_mov_b32 m0, s65
	s_nop 0
	s_add_u32 s100, s48, 0x80
	s_addc_u32 s101, s49, 0
	global_load_lds_dwordx4 v132, s[100:101]
	s_add_i32 s11, s11, 2
	s_add_u32 s9, s9, 0x100
	s_addc_u32 s10, s10, 0
	s_add_u32 s44, s44, 0x100
	s_addc_u32 s45, s45, 0
	s_add_u32 s12, s44, 0xfff80080
	s_addc_u32 s13, s45, -1
	s_cmp_eq_u32 s11, 28
	s_cselect_b32 s49, s5, s13
	s_cselect_b32 s48, s6, s12
	s_cselect_b32 s47, s7, s10
	s_cselect_b32 s46, s8, s9
	s_cmp_gt_u32 s11, 29
	s_waitcnt vmcnt(8)
	s_waitcnt lgkmcnt(0)
	s_barrier
	s_setprio 1
	v_mfma_f32_16x16x32_bf16 v[64:67], v[142:145], v[184:187], v[64:67]
	v_mfma_f32_16x16x32_bf16 v[56:59], v[150:153], v[184:187], v[56:59]
	v_mfma_f32_16x16x32_bf16 v[48:51], v[142:145], v[192:195], v[48:51]
	v_mfma_f32_16x16x32_bf16 v[40:43], v[150:153], v[192:195], v[40:43]
	v_mfma_f32_16x16x32_bf16 v[32:35], v[142:145], v[200:203], v[32:35]
	v_mfma_f32_16x16x32_bf16 v[24:27], v[150:153], v[200:203], v[24:27]
	v_mfma_f32_16x16x32_bf16 v[16:19], v[142:145], v[208:211], v[16:19]
	v_mfma_f32_16x16x32_bf16 v[8:11], v[150:153], v[208:211], v[8:11]
	v_mfma_f32_16x16x32_bf16 v[64:67], v[146:149], v[188:191], v[64:67]
	v_mfma_f32_16x16x32_bf16 v[56:59], v[154:157], v[188:191], v[56:59]
	v_mfma_f32_16x16x32_bf16 v[48:51], v[146:149], v[196:199], v[48:51]
	v_mfma_f32_16x16x32_bf16 v[40:43], v[154:157], v[196:199], v[40:43]
	v_mfma_f32_16x16x32_bf16 v[32:35], v[146:149], v[204:207], v[32:35]
	v_mfma_f32_16x16x32_bf16 v[24:27], v[154:157], v[204:207], v[24:27]
	v_mfma_f32_16x16x32_bf16 v[16:19], v[146:149], v[212:215], v[16:19]
	v_mfma_f32_16x16x32_bf16 v[8:11], v[154:157], v[212:215], v[8:11]
	v_mfma_f32_16x16x32_bf16 v[60:63], v[168:171], v[184:187], v[60:63]
	v_mfma_f32_16x16x32_bf16 v[52:55], v[176:179], v[184:187], v[52:55]
	v_mfma_f32_16x16x32_bf16 v[44:47], v[168:171], v[192:195], v[44:47]
	v_mfma_f32_16x16x32_bf16 v[36:39], v[176:179], v[192:195], v[36:39]
	v_mfma_f32_16x16x32_bf16 v[28:31], v[168:171], v[200:203], v[28:31]
	v_mfma_f32_16x16x32_bf16 v[20:23], v[176:179], v[200:203], v[20:23]
	v_mfma_f32_16x16x32_bf16 v[12:15], v[168:171], v[208:211], v[12:15]
	v_mfma_f32_16x16x32_bf16 v[4:7], v[176:179], v[208:211], v[4:7]
	v_mfma_f32_16x16x32_bf16 v[60:63], v[172:175], v[188:191], v[60:63]
	v_mfma_f32_16x16x32_bf16 v[52:55], v[180:183], v[188:191], v[52:55]
	v_mfma_f32_16x16x32_bf16 v[44:47], v[172:175], v[196:199], v[44:47]
	v_mfma_f32_16x16x32_bf16 v[36:39], v[180:183], v[196:199], v[36:39]
	v_mfma_f32_16x16x32_bf16 v[28:31], v[172:175], v[204:207], v[28:31]
	v_mfma_f32_16x16x32_bf16 v[20:23], v[180:183], v[204:207], v[20:23]
	v_mfma_f32_16x16x32_bf16 v[12:15], v[172:175], v[212:215], v[12:15]
	v_mfma_f32_16x16x32_bf16 v[4:7], v[180:183], v[212:215], v[4:7]
	s_barrier
	s_setprio 0
	s_cbranch_scc0 .LBB0_1066
	s_and_b64 vcc, exec, s[22:23]
	s_cbranch_vccz .LBB0_1069
	s_nop 0
